# grid barrier: the last XCD leader no longer bumps the (now unused) generation word before its acquire
# speedup vs baseline: 1.0067x; 1.0021x over previous
.LBB0_1940:
	s_or_b64 exec, exec, s[20:21]
	s_and_saveexec_b64 s[20:21], s[24:25]
	s_cbranch_execz .LBB0_1942
	s_nop 0
